# grid barrier: the XCD's last arriver invalidates L2 once (right after its writeback, before signalling); every workgroup then invalidates only its CU L1 (buffer_inv sc0) instead of L2
# speedup vs baseline: 1.0535x; 1.0169x over previous
.Lgb_have_counts:
	s_add_i32 s12, s9, 1
	s_mul_i32 s13, s10, s12
	s_mul_i32 s14, s11, s12
	s_lshl_b32 s15, s8, 8
	s_add_u32 s16, s6, s15
	s_addc_u32 s17, s7, 0
	s_add_u32 s16, s16, 0x1400
	s_addc_u32 s17, s17, 0
	global_atomic_add v3, v1, v2, s[16:17] sc0
	s_waitcnt vmcnt(0)
	v_readfirstlane_b32 s15, v3
	s_add_i32 s15, s15, 1
	s_cmp_lg_u32 s15, s13
	s_cbranch_scc1 .Lgb_wait
	buffer_wbl2 sc1
	s_waitcnt vmcnt(0)
	buffer_inv sc1
	global_atomic_add v1, v2, s[18:19]

.Lgb_done:
	buffer_inv sc0
	v_writelane_b32 v255, s12, 21
